# code placement: the ten GEMM K-loop heads aligned to 64 bytes
# baseline (speedup 1.0000x reference)
; template <class Epi, class Sched, bool ALIGN_EPI = false, bool SP2 = false>
; __device__ __forceinline__ void gemm_phase(LAS unsigned char* lds, const Gemm g, const Sched S, const Epi E) {
;     ...
;         const char* nA = has_next ? (const char*)g.A + (size_t)nxt.pm * tstepA + (nxt.pn >= g.asplit ? g.ashift : (size_t)0) : cA; const char* nB = has_next ? (const char*)g.Bt + (size_t)nxt.pn * tstepB : cB;
; #pragma nounroll
;         for (int t = 0; t < nt; t += 2) {
;     ...
; #pragma unroll
;         for (int a = 0; a < 2; ++a)
; #pragma unroll
;             for (int b = 0; b < 2; ++b)
; #pragma unroll
;                 for (int m = 0; m < 4; ++m)
; #pragma unroll
;                     for (int n = 0; n < 2; ++n) acc[a][b][m][n] = (f32x4){0.f, 0.f, 0.f, 0.f};
;         cur = nxt; cA = nA; cB = nB; ++ui;
.LBB0_622:
	s_ashr_i32 s61, s60, 31
	s_lshl_b64 s[34:35], s[60:61], 19
	s_add_u32 s62, s48, s34
	s_addc_u32 s63, s49, s35
	s_and_b64 s[34:35], s[4:5], exec
	s_cselect_b32 s61, s63, s69
	s_cselect_b32 s80, s62, s68
	s_ashr_i32 s51, s50, 31
	s_lshl_b64 s[34:35], s[50:51], 19
	s_add_u32 s64, s6, s34
	s_addc_u32 s65, s7, s35
	s_and_b64 s[34:35], s[4:5], exec
	s_cselect_b32 s51, s65, s71
	s_cselect_b32 s81, s64, s70
	s_add_u32 s68, s68, 0x40080
	s_addc_u32 s69, s69, 0
	s_add_u32 s82, s70, 0x100
	v_mov_b32_e32 v0, 0
	s_addc_u32 s83, s71, 0
	s_mov_b32 s84, -2
	v_mov_b32_e32 v1, v0
	v_mov_b32_e32 v2, v0
	v_mov_b32_e32 v3, v0
	v_mov_b32_e32 v4, v0
	v_mov_b32_e32 v5, v0
	v_mov_b32_e32 v6, v0
	v_mov_b32_e32 v7, v0
	v_mov_b32_e32 v16, v0
	v_mov_b32_e32 v17, v0
	v_mov_b32_e32 v18, v0
	v_mov_b32_e32 v19, v0
	v_mov_b32_e32 v20, v0
	v_mov_b32_e32 v21, v0
	v_mov_b32_e32 v22, v0
	v_mov_b32_e32 v23, v0
	v_mov_b32_e32 v32, v0
	v_mov_b32_e32 v33, v0
	v_mov_b32_e32 v34, v0
	v_mov_b32_e32 v35, v0
	v_mov_b32_e32 v36, v0
	v_mov_b32_e32 v37, v0
	v_mov_b32_e32 v38, v0
	v_mov_b32_e32 v39, v0
	v_mov_b32_e32 v48, v0
	v_mov_b32_e32 v49, v0
	v_mov_b32_e32 v50, v0
	v_mov_b32_e32 v51, v0
	v_mov_b32_e32 v52, v0
	v_mov_b32_e32 v53, v0
	v_mov_b32_e32 v54, v0
	v_mov_b32_e32 v55, v0
	v_mov_b32_e32 v8, v0
	v_mov_b32_e32 v9, v0
	v_mov_b32_e32 v10, v0
	v_mov_b32_e32 v11, v0
	v_mov_b32_e32 v12, v0
	v_mov_b32_e32 v13, v0
	v_mov_b32_e32 v14, v0
	v_mov_b32_e32 v15, v0
	v_mov_b32_e32 v24, v0
	v_mov_b32_e32 v25, v0
	v_mov_b32_e32 v26, v0
	v_mov_b32_e32 v27, v0
	v_mov_b32_e32 v28, v0
	v_mov_b32_e32 v29, v0
	v_mov_b32_e32 v30, v0
	v_mov_b32_e32 v31, v0
	v_mov_b32_e32 v40, v0
	v_mov_b32_e32 v41, v0
	v_mov_b32_e32 v42, v0
	v_mov_b32_e32 v43, v0
	v_mov_b32_e32 v44, v0
	v_mov_b32_e32 v45, v0
	v_mov_b32_e32 v46, v0
	v_mov_b32_e32 v47, v0
	v_mov_b32_e32 v56, v0
	v_mov_b32_e32 v57, v0
	v_mov_b32_e32 v58, v0
	v_mov_b32_e32 v59, v0
	v_mov_b32_e32 v60, v0
	v_mov_b32_e32 v61, v0
	v_mov_b32_e32 v62, v0
	v_mov_b32_e32 v63, v0
	v_mov_b32_e32 v64, v0
	v_mov_b32_e32 v65, v0
	v_mov_b32_e32 v66, v0
	v_mov_b32_e32 v67, v0
	v_mov_b32_e32 v68, v0
	v_mov_b32_e32 v69, v0
	v_mov_b32_e32 v70, v0
	v_mov_b32_e32 v71, v0
	v_mov_b32_e32 v80, v0
	v_mov_b32_e32 v81, v0
	v_mov_b32_e32 v82, v0
	v_mov_b32_e32 v83, v0
	v_mov_b32_e32 v84, v0
	v_mov_b32_e32 v85, v0
	v_mov_b32_e32 v86, v0
	v_mov_b32_e32 v87, v0
	v_mov_b32_e32 v96, v0
	v_mov_b32_e32 v97, v0
	v_mov_b32_e32 v98, v0
	v_mov_b32_e32 v99, v0
	v_mov_b32_e32 v100, v0
	v_mov_b32_e32 v101, v0
	v_mov_b32_e32 v102, v0
	v_mov_b32_e32 v103, v0
	v_mov_b32_e32 v112, v0
	v_mov_b32_e32 v113, v0
	v_mov_b32_e32 v114, v0
	v_mov_b32_e32 v115, v0
	v_mov_b32_e32 v116, v0
	v_mov_b32_e32 v117, v0
	v_mov_b32_e32 v118, v0
	v_mov_b32_e32 v119, v0
	v_mov_b32_e32 v72, v0
	v_mov_b32_e32 v73, v0
	v_mov_b32_e32 v74, v0
	v_mov_b32_e32 v75, v0
	v_mov_b32_e32 v76, v0
	v_mov_b32_e32 v77, v0
	v_mov_b32_e32 v78, v0
	v_mov_b32_e32 v79, v0
	v_mov_b32_e32 v88, v0
	v_mov_b32_e32 v89, v0
	v_mov_b32_e32 v90, v0
	v_mov_b32_e32 v91, v0
	v_mov_b32_e32 v92, v0
	v_mov_b32_e32 v93, v0
	v_mov_b32_e32 v94, v0
	v_mov_b32_e32 v95, v0
	v_mov_b32_e32 v104, v0
	v_mov_b32_e32 v105, v0
	v_mov_b32_e32 v106, v0
	v_mov_b32_e32 v107, v0
	v_mov_b32_e32 v108, v0
	v_mov_b32_e32 v109, v0
	v_mov_b32_e32 v110, v0
	v_mov_b32_e32 v111, v0
	v_mov_b32_e32 v120, v0
	v_mov_b32_e32 v121, v0
	v_mov_b32_e32 v122, v0
	v_mov_b32_e32 v123, v0
	v_mov_b32_e32 v124, v0
	v_mov_b32_e32 v125, v0
	v_mov_b32_e32 v126, v0
	v_mov_b32_e32 v127, v0
	.p2align	6

; template <class Epi, class Sched, bool ALIGN_EPI = false, bool SP2 = false>
; __device__ __forceinline__ void gemm_phase(LAS unsigned char* lds, const Gemm g, const Sched S, const Epi E) {
;     ...
; #pragma unroll
;         for (int a = 0; a < 2; ++a)
; #pragma unroll
;             for (int b = 0; b < 2; ++b)
; #pragma unroll
;                 for (int m = 0; m < 4; ++m)
; #pragma unroll
;                     for (int n = 0; n < 2; ++n) acc[a][b][m][n] = (f32x4){0.f, 0.f, 0.f, 0.f};
;         cur = nxt; cA = nA; cB = nB; ++ui;
.LBB0_704:
	s_add_u32 s86, s74, 0x100
	v_mov_b32_e32 v0, 0
	s_addc_u32 s87, s75, 0
	s_mov_b32 s88, -2
	s_waitcnt lgkmcnt(0)
	v_mov_b32_e32 v1, v0
	v_mov_b32_e32 v2, v0
	v_mov_b32_e32 v3, v0
	v_mov_b32_e32 v4, v0
	v_mov_b32_e32 v5, v0
	v_mov_b32_e32 v6, v0
	v_mov_b32_e32 v7, v0
	v_mov_b32_e32 v16, v0
	v_mov_b32_e32 v17, v0
	v_mov_b32_e32 v18, v0
	v_mov_b32_e32 v19, v0
	v_mov_b32_e32 v20, v0
	v_mov_b32_e32 v21, v0
	v_mov_b32_e32 v22, v0
	v_mov_b32_e32 v23, v0
	v_mov_b32_e32 v32, v0
	v_mov_b32_e32 v33, v0
	v_mov_b32_e32 v34, v0
	v_mov_b32_e32 v35, v0
	v_mov_b32_e32 v36, v0
	v_mov_b32_e32 v37, v0
	v_mov_b32_e32 v38, v0
	v_mov_b32_e32 v39, v0
	v_mov_b32_e32 v48, v0
	v_mov_b32_e32 v49, v0
	v_mov_b32_e32 v50, v0
	v_mov_b32_e32 v51, v0
	v_mov_b32_e32 v52, v0
	v_mov_b32_e32 v53, v0
	v_mov_b32_e32 v54, v0
	v_mov_b32_e32 v55, v0
	v_mov_b32_e32 v8, v0
	v_mov_b32_e32 v9, v0
	v_mov_b32_e32 v10, v0
	v_mov_b32_e32 v11, v0
	v_mov_b32_e32 v12, v0
	v_mov_b32_e32 v13, v0
	v_mov_b32_e32 v14, v0
	v_mov_b32_e32 v15, v0
	v_mov_b32_e32 v24, v0
	v_mov_b32_e32 v25, v0
	v_mov_b32_e32 v26, v0
	v_mov_b32_e32 v27, v0
	v_mov_b32_e32 v28, v0
	v_mov_b32_e32 v29, v0
	v_mov_b32_e32 v30, v0
	v_mov_b32_e32 v31, v0
	v_mov_b32_e32 v40, v0
	v_mov_b32_e32 v41, v0
	v_mov_b32_e32 v42, v0
	v_mov_b32_e32 v43, v0
	v_mov_b32_e32 v44, v0
	v_mov_b32_e32 v45, v0
	v_mov_b32_e32 v46, v0
	v_mov_b32_e32 v47, v0
	v_mov_b32_e32 v56, v0
	v_mov_b32_e32 v57, v0
	v_mov_b32_e32 v58, v0
	v_mov_b32_e32 v59, v0
	v_mov_b32_e32 v60, v0
	v_mov_b32_e32 v61, v0
	v_mov_b32_e32 v62, v0
	v_mov_b32_e32 v63, v0
	v_mov_b32_e32 v64, v0
	v_mov_b32_e32 v65, v0
	v_mov_b32_e32 v66, v0
	v_mov_b32_e32 v67, v0
	v_mov_b32_e32 v68, v0
	v_mov_b32_e32 v69, v0
	v_mov_b32_e32 v70, v0
	v_mov_b32_e32 v71, v0
	v_mov_b32_e32 v80, v0
	v_mov_b32_e32 v81, v0
	v_mov_b32_e32 v82, v0
	v_mov_b32_e32 v83, v0
	v_mov_b32_e32 v84, v0
	v_mov_b32_e32 v85, v0
	v_mov_b32_e32 v86, v0
	v_mov_b32_e32 v87, v0
	v_mov_b32_e32 v96, v0
	v_mov_b32_e32 v97, v0
	v_mov_b32_e32 v98, v0
	v_mov_b32_e32 v99, v0
	v_mov_b32_e32 v100, v0
	v_mov_b32_e32 v101, v0
	v_mov_b32_e32 v102, v0
	v_mov_b32_e32 v103, v0
	v_mov_b32_e32 v112, v0
	v_mov_b32_e32 v113, v0
	v_mov_b32_e32 v114, v0
	v_mov_b32_e32 v115, v0
	v_mov_b32_e32 v116, v0
	v_mov_b32_e32 v117, v0
	v_mov_b32_e32 v118, v0
	v_mov_b32_e32 v119, v0
	v_mov_b32_e32 v72, v0
	v_mov_b32_e32 v73, v0
	v_mov_b32_e32 v74, v0
	v_mov_b32_e32 v75, v0
	v_mov_b32_e32 v76, v0
	v_mov_b32_e32 v77, v0
	v_mov_b32_e32 v78, v0
	v_mov_b32_e32 v79, v0
	v_mov_b32_e32 v88, v0
	v_mov_b32_e32 v89, v0
	v_mov_b32_e32 v90, v0
	v_mov_b32_e32 v91, v0
	v_mov_b32_e32 v92, v0
	v_mov_b32_e32 v93, v0
	v_mov_b32_e32 v94, v0
	v_mov_b32_e32 v95, v0
	v_mov_b32_e32 v104, v0
	v_mov_b32_e32 v105, v0
	v_mov_b32_e32 v106, v0
	v_mov_b32_e32 v107, v0
	v_mov_b32_e32 v108, v0
	v_mov_b32_e32 v109, v0
	v_mov_b32_e32 v110, v0
	v_mov_b32_e32 v111, v0
	v_mov_b32_e32 v120, v0
	v_mov_b32_e32 v121, v0
	v_mov_b32_e32 v122, v0
	v_mov_b32_e32 v123, v0
	v_mov_b32_e32 v124, v0
	v_mov_b32_e32 v125, v0
	v_mov_b32_e32 v126, v0
	v_mov_b32_e32 v127, v0
	.p2align	6

; template <class Epi, class Sched, bool ALIGN_EPI = false, bool SP2 = false>
; __device__ __forceinline__ void gemm_phase(LAS unsigned char* lds, const Gemm g, const Sched S, const Epi E) {
;     ...
; #pragma unroll
;         for (int a = 0; a < 2; ++a)
; #pragma unroll
;             for (int b = 0; b < 2; ++b)
; #pragma unroll
;                 for (int m = 0; m < 4; ++m)
; #pragma unroll
;                     for (int n = 0; n < 2; ++n) acc[a][b][m][n] = (f32x4){0.f, 0.f, 0.f, 0.f};
;         cur = nxt; cA = nA; cB = nB; ++ui;
.LBB0_790:
	s_ashr_i32 s63, s62, 31
	s_lshl_b64 s[34:35], s[62:63], 20
	s_add_u32 s66, s24, s34
	s_addc_u32 s67, s25, s35
	s_and_b64 s[34:35], s[8:9], exec
	s_cselect_b32 s11, s67, s73
	s_cselect_b32 s63, s66, s72
	s_ashr_i32 s61, s60, 31
	s_lshl_b64 s[34:35], s[60:61], 19
	s_add_u32 s68, s18, s34
	s_addc_u32 s69, s19, s35
	s_and_b64 s[34:35], s[8:9], exec
	s_cselect_b32 s61, s69, s75
	s_cselect_b32 s71, s68, s74
	s_add_u32 s72, s72, 0x80080
	s_addc_u32 s73, s73, 0
	s_add_u32 s86, s74, 0x100
	v_mov_b32_e32 v0, 0
	s_addc_u32 s87, s75, 0
	s_mov_b32 s88, -2
	v_mov_b32_e32 v1, v0
	v_mov_b32_e32 v2, v0
	v_mov_b32_e32 v3, v0
	v_mov_b32_e32 v4, v0
	v_mov_b32_e32 v5, v0
	v_mov_b32_e32 v6, v0
	v_mov_b32_e32 v7, v0
	v_mov_b32_e32 v16, v0
	v_mov_b32_e32 v17, v0
	v_mov_b32_e32 v18, v0
	v_mov_b32_e32 v19, v0
	v_mov_b32_e32 v20, v0
	v_mov_b32_e32 v21, v0
	v_mov_b32_e32 v22, v0
	v_mov_b32_e32 v23, v0
	v_mov_b32_e32 v32, v0
	v_mov_b32_e32 v33, v0
	v_mov_b32_e32 v34, v0
	v_mov_b32_e32 v35, v0
	v_mov_b32_e32 v36, v0
	v_mov_b32_e32 v37, v0
	v_mov_b32_e32 v38, v0
	v_mov_b32_e32 v39, v0
	v_mov_b32_e32 v48, v0
	v_mov_b32_e32 v49, v0
	v_mov_b32_e32 v50, v0
	v_mov_b32_e32 v51, v0
	v_mov_b32_e32 v52, v0
	v_mov_b32_e32 v53, v0
	v_mov_b32_e32 v54, v0
	v_mov_b32_e32 v55, v0
	v_mov_b32_e32 v8, v0
	v_mov_b32_e32 v9, v0
	v_mov_b32_e32 v10, v0
	v_mov_b32_e32 v11, v0
	v_mov_b32_e32 v12, v0
	v_mov_b32_e32 v13, v0
	v_mov_b32_e32 v14, v0
	v_mov_b32_e32 v15, v0
	v_mov_b32_e32 v24, v0
	v_mov_b32_e32 v25, v0
	v_mov_b32_e32 v26, v0
	v_mov_b32_e32 v27, v0
	v_mov_b32_e32 v28, v0
	v_mov_b32_e32 v29, v0
	v_mov_b32_e32 v30, v0
	v_mov_b32_e32 v31, v0
	v_mov_b32_e32 v40, v0
	v_mov_b32_e32 v41, v0
	v_mov_b32_e32 v42, v0
	v_mov_b32_e32 v43, v0
	v_mov_b32_e32 v44, v0
	v_mov_b32_e32 v45, v0
	v_mov_b32_e32 v46, v0
	v_mov_b32_e32 v47, v0
	v_mov_b32_e32 v56, v0
	v_mov_b32_e32 v57, v0
	v_mov_b32_e32 v58, v0
	v_mov_b32_e32 v59, v0
	v_mov_b32_e32 v60, v0
	v_mov_b32_e32 v61, v0
	v_mov_b32_e32 v62, v0
	v_mov_b32_e32 v63, v0
	v_mov_b32_e32 v64, v0
	v_mov_b32_e32 v65, v0
	v_mov_b32_e32 v66, v0
	v_mov_b32_e32 v67, v0
	v_mov_b32_e32 v68, v0
	v_mov_b32_e32 v69, v0
	v_mov_b32_e32 v70, v0
	v_mov_b32_e32 v71, v0
	v_mov_b32_e32 v80, v0
	v_mov_b32_e32 v81, v0
	v_mov_b32_e32 v82, v0
	v_mov_b32_e32 v83, v0
	v_mov_b32_e32 v84, v0
	v_mov_b32_e32 v85, v0
	v_mov_b32_e32 v86, v0
	v_mov_b32_e32 v87, v0
	v_mov_b32_e32 v96, v0
	v_mov_b32_e32 v97, v0
	v_mov_b32_e32 v98, v0
	v_mov_b32_e32 v99, v0
	v_mov_b32_e32 v100, v0
	v_mov_b32_e32 v101, v0
	v_mov_b32_e32 v102, v0
	v_mov_b32_e32 v103, v0
	v_mov_b32_e32 v112, v0
	v_mov_b32_e32 v113, v0
	v_mov_b32_e32 v114, v0
	v_mov_b32_e32 v115, v0
	v_mov_b32_e32 v116, v0
	v_mov_b32_e32 v117, v0
	v_mov_b32_e32 v118, v0
	v_mov_b32_e32 v119, v0
	v_mov_b32_e32 v72, v0
	v_mov_b32_e32 v73, v0
	v_mov_b32_e32 v74, v0
	v_mov_b32_e32 v75, v0
	v_mov_b32_e32 v76, v0
	v_mov_b32_e32 v77, v0
	v_mov_b32_e32 v78, v0
	v_mov_b32_e32 v79, v0
	v_mov_b32_e32 v88, v0
	v_mov_b32_e32 v89, v0
	v_mov_b32_e32 v90, v0
	v_mov_b32_e32 v91, v0
	v_mov_b32_e32 v92, v0
	v_mov_b32_e32 v93, v0
	v_mov_b32_e32 v94, v0
	v_mov_b32_e32 v95, v0
	v_mov_b32_e32 v104, v0
	v_mov_b32_e32 v105, v0
	v_mov_b32_e32 v106, v0
	v_mov_b32_e32 v107, v0
	v_mov_b32_e32 v108, v0
	v_mov_b32_e32 v109, v0
	v_mov_b32_e32 v110, v0
	v_mov_b32_e32 v111, v0
	v_mov_b32_e32 v120, v0
	v_mov_b32_e32 v121, v0
	v_mov_b32_e32 v122, v0
	v_mov_b32_e32 v123, v0
	v_mov_b32_e32 v124, v0
	v_mov_b32_e32 v125, v0
	v_mov_b32_e32 v126, v0
	v_mov_b32_e32 v127, v0
	s_lshl_b32 s100, s10, 8
	s_add_i32 s100, s100, s31
	v_or_b32_e32 v252, s100, v150
	v_ashrrev_i32_e32 v253, 31, v252
	v_lshl_add_u64 v[252:253], v[252:253], 2, s[26:27]
	global_load_dword v244, v[252:253], off
	global_load_dword v245, v[252:253], off offset:64
	global_load_dword v246, v[252:253], off offset:128
	global_load_dword v247, v[252:253], off offset:192
	global_load_dword v248, v[252:253], off offset:512
	global_load_dword v249, v[252:253], off offset:576
	global_load_dword v250, v[252:253], off offset:640
	global_load_dword v251, v[252:253], off offset:704
	.p2align	6

; template <class Epi, class Sched, bool ALIGN_EPI = false, bool SP2 = false>
; __device__ __forceinline__ void gemm_phase(LAS unsigned char* lds, const Gemm g, const Sched S, const Epi E) {
;     ...
; #pragma unroll
;         for (int a = 0; a < 2; ++a)
; #pragma unroll
;             for (int b = 0; b < 2; ++b)
; #pragma unroll
;                 for (int m = 0; m < 4; ++m)
; #pragma unroll
;                     for (int n = 0; n < 2; ++n) acc[a][b][m][n] = (f32x4){0.f, 0.f, 0.f, 0.f};
;         cur = nxt; cA = nA; cB = nB; ++ui;
.LBB0_1406:
	s_add_u32 s78, s66, 0x100
	v_mov_b32_e32 v0, 0
	s_addc_u32 s79, s67, 0
	s_mov_b32 s80, -2
	v_mov_b32_e32 v1, v0
	v_mov_b32_e32 v2, v0
	v_mov_b32_e32 v3, v0
	v_mov_b32_e32 v4, v0
	v_mov_b32_e32 v5, v0
	v_mov_b32_e32 v6, v0
	v_mov_b32_e32 v7, v0
	v_mov_b32_e32 v16, v0
	v_mov_b32_e32 v17, v0
	v_mov_b32_e32 v18, v0
	v_mov_b32_e32 v19, v0
	v_mov_b32_e32 v20, v0
	v_mov_b32_e32 v21, v0
	v_mov_b32_e32 v22, v0
	v_mov_b32_e32 v23, v0
	v_mov_b32_e32 v32, v0
	v_mov_b32_e32 v33, v0
	v_mov_b32_e32 v34, v0
	v_mov_b32_e32 v35, v0
	v_mov_b32_e32 v36, v0
	v_mov_b32_e32 v37, v0
	v_mov_b32_e32 v38, v0
	v_mov_b32_e32 v39, v0
	v_mov_b32_e32 v48, v0
	v_mov_b32_e32 v49, v0
	v_mov_b32_e32 v50, v0
	v_mov_b32_e32 v51, v0
	v_mov_b32_e32 v52, v0
	v_mov_b32_e32 v53, v0
	v_mov_b32_e32 v54, v0
	v_mov_b32_e32 v55, v0
	v_mov_b32_e32 v8, v0
	v_mov_b32_e32 v9, v0
	v_mov_b32_e32 v10, v0
	v_mov_b32_e32 v11, v0
	v_mov_b32_e32 v12, v0
	v_mov_b32_e32 v13, v0
	v_mov_b32_e32 v14, v0
	v_mov_b32_e32 v15, v0
	v_mov_b32_e32 v24, v0
	v_mov_b32_e32 v25, v0
	v_mov_b32_e32 v26, v0
	v_mov_b32_e32 v27, v0
	v_mov_b32_e32 v28, v0
	v_mov_b32_e32 v29, v0
	v_mov_b32_e32 v30, v0
	v_mov_b32_e32 v31, v0
	v_mov_b32_e32 v40, v0
	v_mov_b32_e32 v41, v0
	v_mov_b32_e32 v42, v0
	v_mov_b32_e32 v43, v0
	v_mov_b32_e32 v44, v0
	v_mov_b32_e32 v45, v0
	v_mov_b32_e32 v46, v0
	v_mov_b32_e32 v47, v0
	v_mov_b32_e32 v56, v0
	v_mov_b32_e32 v57, v0
	v_mov_b32_e32 v58, v0
	v_mov_b32_e32 v59, v0
	v_mov_b32_e32 v60, v0
	v_mov_b32_e32 v61, v0
	v_mov_b32_e32 v62, v0
	v_mov_b32_e32 v63, v0
	v_mov_b32_e32 v64, v0
	v_mov_b32_e32 v65, v0
	v_mov_b32_e32 v66, v0
	v_mov_b32_e32 v67, v0
	v_mov_b32_e32 v68, v0
	v_mov_b32_e32 v69, v0
	v_mov_b32_e32 v70, v0
	v_mov_b32_e32 v71, v0
	v_mov_b32_e32 v80, v0
	v_mov_b32_e32 v81, v0
	v_mov_b32_e32 v82, v0
	v_mov_b32_e32 v83, v0
	v_mov_b32_e32 v84, v0
	v_mov_b32_e32 v85, v0
	v_mov_b32_e32 v86, v0
	v_mov_b32_e32 v87, v0
	v_mov_b32_e32 v96, v0
	v_mov_b32_e32 v97, v0
	v_mov_b32_e32 v98, v0
	v_mov_b32_e32 v99, v0
	v_mov_b32_e32 v100, v0
	v_mov_b32_e32 v101, v0
	v_mov_b32_e32 v102, v0
	v_mov_b32_e32 v103, v0
	v_mov_b32_e32 v112, v0
	v_mov_b32_e32 v113, v0
	v_mov_b32_e32 v114, v0
	v_mov_b32_e32 v115, v0
	v_mov_b32_e32 v116, v0
	v_mov_b32_e32 v117, v0
	v_mov_b32_e32 v118, v0
	v_mov_b32_e32 v119, v0
	v_mov_b32_e32 v72, v0
	v_mov_b32_e32 v73, v0
	v_mov_b32_e32 v74, v0
	v_mov_b32_e32 v75, v0
	v_mov_b32_e32 v76, v0
	v_mov_b32_e32 v77, v0
	v_mov_b32_e32 v78, v0
	v_mov_b32_e32 v79, v0
	v_mov_b32_e32 v88, v0
	v_mov_b32_e32 v89, v0
	v_mov_b32_e32 v90, v0
	v_mov_b32_e32 v91, v0
	v_mov_b32_e32 v92, v0
	v_mov_b32_e32 v93, v0
	v_mov_b32_e32 v94, v0
	v_mov_b32_e32 v95, v0
	v_mov_b32_e32 v104, v0
	v_mov_b32_e32 v105, v0
	v_mov_b32_e32 v106, v0
	v_mov_b32_e32 v107, v0
	v_mov_b32_e32 v108, v0
	v_mov_b32_e32 v109, v0
	v_mov_b32_e32 v110, v0
	v_mov_b32_e32 v111, v0
	v_mov_b32_e32 v120, v0
	v_mov_b32_e32 v121, v0
	v_mov_b32_e32 v122, v0
	v_mov_b32_e32 v123, v0
	v_mov_b32_e32 v124, v0
	v_mov_b32_e32 v125, v0
	v_mov_b32_e32 v126, v0
	v_mov_b32_e32 v127, v0
	.p2align	6

; template <class Epi, class Sched, bool ALIGN_EPI = false, bool SP2 = false>
; __device__ __forceinline__ void gemm_phase(LAS unsigned char* lds, const Gemm g, const Sched S, const Epi E) {
;     ...
; #pragma unroll
;         for (int a = 0; a < 2; ++a)
; #pragma unroll
;             for (int b = 0; b < 2; ++b)
; #pragma unroll
;                 for (int m = 0; m < 4; ++m)
; #pragma unroll
;                     for (int n = 0; n < 2; ++n) acc[a][b][m][n] = (f32x4){0.f, 0.f, 0.f, 0.f};
;         cur = nxt; cA = nA; cB = nB; ++ui;
.LBB0_1436:
	s_ashr_i32 s57, s56, 31
	s_lshl_b64 s[12:13], s[56:57], 17
	s_add_u32 s64, s52, s12
	s_addc_u32 s65, s53, s13
	s_and_b64 s[8:9], s[8:9], exec
	v_mov_b32_e32 v0, 0
	s_cselect_b32 s57, s65, s67
	s_cselect_b32 s89, s64, s66
	s_mov_b64 s[72:73], 0
	s_mov_b64 s[8:9], -1
	s_mov_b64 s[70:71], 0
	v_mov_b32_e32 v1, v0
	v_mov_b32_e32 v2, v0
	v_mov_b32_e32 v3, v0
	v_mov_b32_e32 v4, v0
	v_mov_b32_e32 v5, v0
	v_mov_b32_e32 v6, v0
	v_mov_b32_e32 v7, v0
	s_waitcnt vmcnt(0)
	v_mov_b32_e32 v16, v0
	v_mov_b32_e32 v17, v0
	v_mov_b32_e32 v18, v0
	v_mov_b32_e32 v19, v0
	v_mov_b32_e32 v20, v0
	v_mov_b32_e32 v21, v0
	v_mov_b32_e32 v22, v0
	v_mov_b32_e32 v23, v0
	v_mov_b32_e32 v32, v0
	v_mov_b32_e32 v33, v0
	v_mov_b32_e32 v34, v0
	v_mov_b32_e32 v35, v0
	v_mov_b32_e32 v36, v0
	v_mov_b32_e32 v37, v0
	v_mov_b32_e32 v38, v0
	v_mov_b32_e32 v39, v0
	v_mov_b32_e32 v48, v0
	v_mov_b32_e32 v49, v0
	v_mov_b32_e32 v50, v0
	v_mov_b32_e32 v51, v0
	v_mov_b32_e32 v52, v0
	v_mov_b32_e32 v53, v0
	v_mov_b32_e32 v54, v0
	v_mov_b32_e32 v55, v0
	v_mov_b32_e32 v8, v0
	v_mov_b32_e32 v9, v0
	v_mov_b32_e32 v10, v0
	v_mov_b32_e32 v11, v0
	v_mov_b32_e32 v12, v0
	v_mov_b32_e32 v13, v0
	v_mov_b32_e32 v14, v0
	v_mov_b32_e32 v15, v0
	v_mov_b32_e32 v24, v0
	v_mov_b32_e32 v25, v0
	v_mov_b32_e32 v26, v0
	v_mov_b32_e32 v27, v0
	v_mov_b32_e32 v28, v0
	v_mov_b32_e32 v29, v0
	v_mov_b32_e32 v30, v0
	v_mov_b32_e32 v31, v0
	v_mov_b32_e32 v40, v0
	v_mov_b32_e32 v41, v0
	v_mov_b32_e32 v42, v0
	v_mov_b32_e32 v43, v0
	v_mov_b32_e32 v44, v0
	v_mov_b32_e32 v45, v0
	v_mov_b32_e32 v46, v0
	v_mov_b32_e32 v47, v0
	v_mov_b32_e32 v56, v0
	v_mov_b32_e32 v57, v0
	v_mov_b32_e32 v58, v0
	v_mov_b32_e32 v59, v0
	v_mov_b32_e32 v60, v0
	v_mov_b32_e32 v61, v0
	v_mov_b32_e32 v62, v0
	v_mov_b32_e32 v63, v0
	v_mov_b32_e32 v64, v0
	v_mov_b32_e32 v65, v0
	v_mov_b32_e32 v66, v0
	v_mov_b32_e32 v67, v0
	v_mov_b32_e32 v68, v0
	v_mov_b32_e32 v69, v0
	v_mov_b32_e32 v70, v0
	v_mov_b32_e32 v71, v0
	v_mov_b32_e32 v80, v0
	v_mov_b32_e32 v81, v0
	v_mov_b32_e32 v82, v0
	v_mov_b32_e32 v83, v0
	v_mov_b32_e32 v84, v0
	v_mov_b32_e32 v85, v0
	v_mov_b32_e32 v86, v0
	v_mov_b32_e32 v87, v0
	v_mov_b32_e32 v96, v0
	v_mov_b32_e32 v97, v0
	v_mov_b32_e32 v98, v0
	v_mov_b32_e32 v99, v0
	v_mov_b32_e32 v100, v0
	v_mov_b32_e32 v101, v0
	v_mov_b32_e32 v102, v0
	v_mov_b32_e32 v103, v0
	v_mov_b32_e32 v112, v0
	v_mov_b32_e32 v113, v0
	v_mov_b32_e32 v114, v0
	v_mov_b32_e32 v115, v0
	v_mov_b32_e32 v116, v0
	v_mov_b32_e32 v117, v0
	v_mov_b32_e32 v118, v0
	v_mov_b32_e32 v119, v0
	v_mov_b32_e32 v72, v0
	v_mov_b32_e32 v73, v0
	v_mov_b32_e32 v74, v0
	v_mov_b32_e32 v75, v0
	v_mov_b32_e32 v76, v0
	v_mov_b32_e32 v77, v0
	v_mov_b32_e32 v78, v0
	v_mov_b32_e32 v79, v0
	v_mov_b32_e32 v88, v0
	v_mov_b32_e32 v89, v0
	v_mov_b32_e32 v90, v0
	v_mov_b32_e32 v91, v0
	v_mov_b32_e32 v92, v0
	v_mov_b32_e32 v93, v0
	v_mov_b32_e32 v94, v0
	v_mov_b32_e32 v95, v0
	v_mov_b32_e32 v104, v0
	v_mov_b32_e32 v105, v0
	v_mov_b32_e32 v106, v0
	v_mov_b32_e32 v107, v0
	v_mov_b32_e32 v108, v0
	v_mov_b32_e32 v109, v0
	v_mov_b32_e32 v110, v0
	v_mov_b32_e32 v111, v0
	v_mov_b32_e32 v120, v0
	v_mov_b32_e32 v121, v0
	v_mov_b32_e32 v122, v0
	v_mov_b32_e32 v123, v0
	v_mov_b32_e32 v124, v0
	v_mov_b32_e32 v125, v0
	v_mov_b32_e32 v126, v0
	v_mov_b32_e32 v127, v0
	.p2align	6

; template <class Epi, class Sched, bool ALIGN_EPI = false, bool SP2 = false>
; __device__ __forceinline__ void gemm_phase(LAS unsigned char* lds, const Gemm g, const Sched S, const Epi E) {
;     ...
;         const char* nA = has_next ? (const char*)g.A + (size_t)nxt.pm * tstepA + (nxt.pn >= g.asplit ? g.ashift : (size_t)0) : cA; const char* nB = has_next ? (const char*)g.Bt + (size_t)nxt.pn * tstepB : cB;
; #pragma nounroll
;         for (int t = 0; t < nt; t += 2) {
;     ...
; #pragma unroll
;         for (int a = 0; a < 2; ++a)
; #pragma unroll
;             for (int b = 0; b < 2; ++b)
; #pragma unroll
;                 for (int m = 0; m < 4; ++m)
; #pragma unroll
;                     for (int n = 0; n < 2; ++n) acc[a][b][m][n] = (f32x4){0.f, 0.f, 0.f, 0.f};
;         cur = nxt; cA = nA; cB = nB; ++ui;
.LBB0_1611:
	s_ashr_i32 s19, s18, 31
	s_lshl_b64 s[34:35], s[18:19], 19
	s_add_u32 s52, s46, s34
	s_addc_u32 s53, s47, s35
	s_and_b64 s[10:11], s[10:11], exec
	s_cselect_b32 s19, s53, s57
	s_cselect_b32 s68, s52, s56
	s_add_u32 s69, s56, 0x100
	v_mov_b32_e32 v0, 0
	s_addc_u32 s70, s57, 0
	s_mov_b32 s71, -2
	v_mov_b32_e32 v1, v0
	v_mov_b32_e32 v2, v0
	v_mov_b32_e32 v3, v0
	v_mov_b32_e32 v4, v0
	v_mov_b32_e32 v5, v0
	v_mov_b32_e32 v6, v0
	v_mov_b32_e32 v7, v0
	v_mov_b32_e32 v8, v0
	v_mov_b32_e32 v9, v0
	v_mov_b32_e32 v10, v0
	v_mov_b32_e32 v11, v0
	v_mov_b32_e32 v12, v0
	v_mov_b32_e32 v13, v0
	v_mov_b32_e32 v14, v0
	v_mov_b32_e32 v15, v0
	v_mov_b32_e32 v24, v0
	v_mov_b32_e32 v25, v0
	v_mov_b32_e32 v26, v0
	v_mov_b32_e32 v27, v0
	v_mov_b32_e32 v28, v0
	v_mov_b32_e32 v29, v0
	v_mov_b32_e32 v30, v0
	v_mov_b32_e32 v31, v0
	v_mov_b32_e32 v40, v0
	v_mov_b32_e32 v41, v0
	v_mov_b32_e32 v42, v0
	v_mov_b32_e32 v43, v0
	v_mov_b32_e32 v44, v0
	v_mov_b32_e32 v45, v0
	v_mov_b32_e32 v46, v0
	v_mov_b32_e32 v47, v0
	v_mov_b32_e32 v16, v0
	v_mov_b32_e32 v17, v0
	v_mov_b32_e32 v18, v0
	v_mov_b32_e32 v19, v0
	v_mov_b32_e32 v20, v0
	v_mov_b32_e32 v21, v0
	v_mov_b32_e32 v22, v0
	v_mov_b32_e32 v23, v0
	v_mov_b32_e32 v32, v0
	v_mov_b32_e32 v33, v0
	v_mov_b32_e32 v34, v0
	v_mov_b32_e32 v35, v0
	v_mov_b32_e32 v36, v0
	v_mov_b32_e32 v37, v0
	v_mov_b32_e32 v38, v0
	v_mov_b32_e32 v39, v0
	v_mov_b32_e32 v48, v0
	v_mov_b32_e32 v49, v0
	v_mov_b32_e32 v50, v0
	v_mov_b32_e32 v51, v0
	v_mov_b32_e32 v52, v0
	v_mov_b32_e32 v53, v0
	v_mov_b32_e32 v54, v0
	v_mov_b32_e32 v55, v0
	v_mov_b32_e32 v56, v0
	v_mov_b32_e32 v57, v0
	v_mov_b32_e32 v58, v0
	v_mov_b32_e32 v59, v0
	v_mov_b32_e32 v60, v0
	v_mov_b32_e32 v61, v0
	v_mov_b32_e32 v62, v0
	v_mov_b32_e32 v63, v0
	v_mov_b32_e32 v64, v0
	v_mov_b32_e32 v65, v0
	v_mov_b32_e32 v66, v0
	v_mov_b32_e32 v67, v0
	v_mov_b32_e32 v68, v0
	v_mov_b32_e32 v69, v0
	v_mov_b32_e32 v70, v0
	v_mov_b32_e32 v71, v0
	v_mov_b32_e32 v72, v0
	v_mov_b32_e32 v73, v0
	v_mov_b32_e32 v74, v0
	v_mov_b32_e32 v75, v0
	v_mov_b32_e32 v76, v0
	v_mov_b32_e32 v77, v0
	v_mov_b32_e32 v78, v0
	v_mov_b32_e32 v79, v0
	v_mov_b32_e32 v88, v0
	v_mov_b32_e32 v89, v0
	v_mov_b32_e32 v90, v0
	v_mov_b32_e32 v91, v0
	v_mov_b32_e32 v92, v0
	v_mov_b32_e32 v93, v0
	v_mov_b32_e32 v94, v0
	v_mov_b32_e32 v95, v0
	v_mov_b32_e32 v104, v0
	v_mov_b32_e32 v105, v0
	v_mov_b32_e32 v106, v0
	v_mov_b32_e32 v107, v0
	v_mov_b32_e32 v108, v0
	v_mov_b32_e32 v109, v0
	v_mov_b32_e32 v110, v0
	v_mov_b32_e32 v111, v0
	v_mov_b32_e32 v80, v0
	v_mov_b32_e32 v81, v0
	v_mov_b32_e32 v82, v0
	v_mov_b32_e32 v83, v0
	v_mov_b32_e32 v84, v0
	v_mov_b32_e32 v85, v0
	v_mov_b32_e32 v86, v0
	v_mov_b32_e32 v87, v0
	v_mov_b32_e32 v96, v0
	v_mov_b32_e32 v97, v0
	v_mov_b32_e32 v98, v0
	v_mov_b32_e32 v99, v0
	v_mov_b32_e32 v100, v0
	v_mov_b32_e32 v101, v0
	v_mov_b32_e32 v102, v0
	v_mov_b32_e32 v103, v0
	v_mov_b32_e32 v112, v0
	v_mov_b32_e32 v113, v0
	v_mov_b32_e32 v114, v0
	v_mov_b32_e32 v115, v0
	v_mov_b32_e32 v116, v0
	v_mov_b32_e32 v117, v0
	v_mov_b32_e32 v118, v0
	v_mov_b32_e32 v119, v0
	v_mov_b32_e32 v120, v0
	v_mov_b32_e32 v121, v0
	v_mov_b32_e32 v122, v0
	v_mov_b32_e32 v123, v0
	v_mov_b32_e32 v124, v0
	v_mov_b32_e32 v125, v0
	v_mov_b32_e32 v126, v0
	v_mov_b32_e32 v127, v0
	.p2align	6

; template <class Epi, class Sched, bool ALIGN_EPI = false, bool SP2 = false>
; __device__ __forceinline__ void gemm_phase(LAS unsigned char* lds, const Gemm g, const Sched S, const Epi E) {
;     ...
;         const char* nA = has_next ? (const char*)g.A + (size_t)nxt.pm * tstepA + (nxt.pn >= g.asplit ? g.ashift : (size_t)0) : cA; const char* nB = has_next ? (const char*)g.Bt + (size_t)nxt.pn * tstepB : cB;
; #pragma nounroll
;         for (int t = 0; t < nt; t += 2) {
;     ...
; #pragma unroll
;         for (int a = 0; a < 2; ++a)
; #pragma unroll
;             for (int b = 0; b < 2; ++b)
; #pragma unroll
;                 for (int m = 0; m < 4; ++m)
; #pragma unroll
;                     for (int n = 0; n < 2; ++n) acc[a][b][m][n] = (f32x4){0.f, 0.f, 0.f, 0.f};
;         cur = nxt; cA = nA; cB = nB; ++ui;
.LBB0_1687:
	s_ashr_i32 s19, s18, 31
	s_lshl_b64 s[34:35], s[18:19], 20
	s_add_u32 s46, s24, s34
	s_addc_u32 s47, s25, s35
	s_and_b64 s[34:35], s[6:7], exec
	s_cselect_b32 s19, s47, s53
	s_cselect_b32 s62, s46, s52
	s_ashr_i32 s17, s16, 31
	s_lshl_b64 s[34:35], s[16:17], 19
	s_add_u32 s48, s42, s34
	s_addc_u32 s49, s43, s35
	s_and_b64 s[34:35], s[6:7], exec
	s_cselect_b32 s17, s49, s55
	s_cselect_b32 s63, s48, s54
	s_add_u32 s52, s52, 0x80080
	s_addc_u32 s53, s53, 0
	s_add_u32 s64, s54, 0x100
	v_mov_b32_e32 v0, 0
	s_addc_u32 s65, s55, 0
	s_mov_b32 s66, -2
	v_mov_b32_e32 v1, v0
	v_mov_b32_e32 v2, v0
	v_mov_b32_e32 v3, v0
	v_mov_b32_e32 v4, v0
	v_mov_b32_e32 v5, v0
	v_mov_b32_e32 v6, v0
	v_mov_b32_e32 v7, v0
	v_mov_b32_e32 v16, v0
	v_mov_b32_e32 v17, v0
	v_mov_b32_e32 v18, v0
	v_mov_b32_e32 v19, v0
	v_mov_b32_e32 v20, v0
	v_mov_b32_e32 v21, v0
	v_mov_b32_e32 v22, v0
	v_mov_b32_e32 v23, v0
	v_mov_b32_e32 v32, v0
	v_mov_b32_e32 v33, v0
	v_mov_b32_e32 v34, v0
	v_mov_b32_e32 v35, v0
	v_mov_b32_e32 v36, v0
	v_mov_b32_e32 v37, v0
	v_mov_b32_e32 v38, v0
	v_mov_b32_e32 v39, v0
	v_mov_b32_e32 v48, v0
	v_mov_b32_e32 v49, v0
	v_mov_b32_e32 v50, v0
	v_mov_b32_e32 v51, v0
	v_mov_b32_e32 v52, v0
	v_mov_b32_e32 v53, v0
	v_mov_b32_e32 v54, v0
	v_mov_b32_e32 v55, v0
	v_mov_b32_e32 v8, v0
	v_mov_b32_e32 v9, v0
	v_mov_b32_e32 v10, v0
	v_mov_b32_e32 v11, v0
	v_mov_b32_e32 v12, v0
	v_mov_b32_e32 v13, v0
	v_mov_b32_e32 v14, v0
	v_mov_b32_e32 v15, v0
	v_mov_b32_e32 v24, v0
	v_mov_b32_e32 v25, v0
	v_mov_b32_e32 v26, v0
	v_mov_b32_e32 v27, v0
	v_mov_b32_e32 v28, v0
	v_mov_b32_e32 v29, v0
	v_mov_b32_e32 v30, v0
	v_mov_b32_e32 v31, v0
	v_mov_b32_e32 v40, v0
	v_mov_b32_e32 v41, v0
	v_mov_b32_e32 v42, v0
	v_mov_b32_e32 v43, v0
	v_mov_b32_e32 v44, v0
	v_mov_b32_e32 v45, v0
	v_mov_b32_e32 v46, v0
	v_mov_b32_e32 v47, v0
	v_mov_b32_e32 v56, v0
	v_mov_b32_e32 v57, v0
	v_mov_b32_e32 v58, v0
	v_mov_b32_e32 v59, v0
	v_mov_b32_e32 v60, v0
	v_mov_b32_e32 v61, v0
	v_mov_b32_e32 v62, v0
	v_mov_b32_e32 v63, v0
	v_mov_b32_e32 v64, v0
	v_mov_b32_e32 v65, v0
	v_mov_b32_e32 v66, v0
	v_mov_b32_e32 v67, v0
	v_mov_b32_e32 v68, v0
	v_mov_b32_e32 v69, v0
	v_mov_b32_e32 v70, v0
	v_mov_b32_e32 v71, v0
	v_mov_b32_e32 v80, v0
	v_mov_b32_e32 v81, v0
	v_mov_b32_e32 v82, v0
	v_mov_b32_e32 v83, v0
	v_mov_b32_e32 v84, v0
	v_mov_b32_e32 v85, v0
	v_mov_b32_e32 v86, v0
	v_mov_b32_e32 v87, v0
	v_mov_b32_e32 v96, v0
	v_mov_b32_e32 v97, v0
	v_mov_b32_e32 v98, v0
	v_mov_b32_e32 v99, v0
	v_mov_b32_e32 v100, v0
	v_mov_b32_e32 v101, v0
	v_mov_b32_e32 v102, v0
	v_mov_b32_e32 v103, v0
	v_mov_b32_e32 v112, v0
	v_mov_b32_e32 v113, v0
	v_mov_b32_e32 v114, v0
	v_mov_b32_e32 v115, v0
	v_mov_b32_e32 v116, v0
	v_mov_b32_e32 v117, v0
	v_mov_b32_e32 v118, v0
	v_mov_b32_e32 v119, v0
	v_mov_b32_e32 v72, v0
	v_mov_b32_e32 v73, v0
	v_mov_b32_e32 v74, v0
	v_mov_b32_e32 v75, v0
	v_mov_b32_e32 v76, v0
	v_mov_b32_e32 v77, v0
	v_mov_b32_e32 v78, v0
	v_mov_b32_e32 v79, v0
	v_mov_b32_e32 v88, v0
	v_mov_b32_e32 v89, v0
	v_mov_b32_e32 v90, v0
	v_mov_b32_e32 v91, v0
	v_mov_b32_e32 v92, v0
	v_mov_b32_e32 v93, v0
	v_mov_b32_e32 v94, v0
	v_mov_b32_e32 v95, v0
	v_mov_b32_e32 v104, v0
	v_mov_b32_e32 v105, v0
	v_mov_b32_e32 v106, v0
	v_mov_b32_e32 v107, v0
	v_mov_b32_e32 v108, v0
	v_mov_b32_e32 v109, v0
	v_mov_b32_e32 v110, v0
	v_mov_b32_e32 v111, v0
	v_mov_b32_e32 v120, v0
	v_mov_b32_e32 v121, v0
	v_mov_b32_e32 v122, v0
	v_mov_b32_e32 v123, v0
	v_mov_b32_e32 v124, v0
	v_mov_b32_e32 v125, v0
	v_mov_b32_e32 v126, v0
	v_mov_b32_e32 v127, v0
	.p2align	6

; template <class Epi, class Sched, bool ALIGN_EPI = false, bool SP2 = false>
; __device__ __forceinline__ void gemm_phase(LAS unsigned char* lds, const Gemm g, const Sched S, const Epi E) {
;     ...
;         const char* nA = has_next ? (const char*)g.A + (size_t)nxt.pm * tstepA + (nxt.pn >= g.asplit ? g.ashift : (size_t)0) : cA; const char* nB = has_next ? (const char*)g.Bt + (size_t)nxt.pn * tstepB : cB;
; #pragma nounroll
;         for (int t = 0; t < nt; t += 2) {
;     ...
; #pragma unroll
;         for (int a = 0; a < 2; ++a)
; #pragma unroll
;             for (int b = 0; b < 2; ++b)
; #pragma unroll
;                 for (int m = 0; m < 4; ++m)
; #pragma unroll
;                     for (int n = 0; n < 2; ++n) acc[a][b][m][n] = (f32x4){0.f, 0.f, 0.f, 0.f};
;         cur = nxt; cA = nA; cB = nB; ++ui;
.LBB0_1765:
	s_ashr_i32 s19, s18, 31
	s_lshl_b64 s[34:35], s[18:19], 19
	s_add_u32 s46, s50, s34
	s_addc_u32 s47, s51, s35
	s_and_b64 s[34:35], s[8:9], exec
	s_cselect_b32 s19, s47, s57
	s_cselect_b32 s53, s46, s56
	s_ashr_i32 s17, s16, 31
	s_lshl_b64 s[34:35], s[16:17], 19
	s_add_u32 s48, s22, s34
	s_addc_u32 s49, s23, s35
	s_and_b64 s[34:35], s[8:9], exec
	s_cselect_b32 s17, s49, s59
	s_cselect_b32 s63, s48, s58
	s_add_u32 s56, s56, 0x40080
	s_addc_u32 s57, s57, 0
	s_add_u32 s64, s58, 0x100
	v_mov_b32_e32 v0, 0
	s_addc_u32 s65, s59, 0
	s_mov_b32 s66, -2
	s_waitcnt lgkmcnt(0)
	v_mov_b32_e32 v1, v0
	v_mov_b32_e32 v2, v0
	v_mov_b32_e32 v3, v0
	v_mov_b32_e32 v4, v0
	v_mov_b32_e32 v5, v0
	v_mov_b32_e32 v6, v0
	v_mov_b32_e32 v7, v0
	v_mov_b32_e32 v16, v0
	v_mov_b32_e32 v17, v0
	v_mov_b32_e32 v18, v0
	v_mov_b32_e32 v19, v0
	v_mov_b32_e32 v20, v0
	v_mov_b32_e32 v21, v0
	v_mov_b32_e32 v22, v0
	v_mov_b32_e32 v23, v0
	v_mov_b32_e32 v32, v0
	v_mov_b32_e32 v33, v0
	v_mov_b32_e32 v34, v0
	v_mov_b32_e32 v35, v0
	v_mov_b32_e32 v36, v0
	v_mov_b32_e32 v37, v0
	v_mov_b32_e32 v38, v0
	v_mov_b32_e32 v39, v0
	v_mov_b32_e32 v48, v0
	v_mov_b32_e32 v49, v0
	v_mov_b32_e32 v50, v0
	v_mov_b32_e32 v51, v0
	v_mov_b32_e32 v52, v0
	v_mov_b32_e32 v53, v0
	v_mov_b32_e32 v54, v0
	v_mov_b32_e32 v55, v0
	v_mov_b32_e32 v8, v0
	v_mov_b32_e32 v9, v0
	v_mov_b32_e32 v10, v0
	v_mov_b32_e32 v11, v0
	v_mov_b32_e32 v12, v0
	v_mov_b32_e32 v13, v0
	v_mov_b32_e32 v14, v0
	v_mov_b32_e32 v15, v0
	v_mov_b32_e32 v24, v0
	v_mov_b32_e32 v25, v0
	v_mov_b32_e32 v26, v0
	v_mov_b32_e32 v27, v0
	v_mov_b32_e32 v28, v0
	v_mov_b32_e32 v29, v0
	v_mov_b32_e32 v30, v0
	v_mov_b32_e32 v31, v0
	v_mov_b32_e32 v40, v0
	v_mov_b32_e32 v41, v0
	v_mov_b32_e32 v42, v0
	v_mov_b32_e32 v43, v0
	v_mov_b32_e32 v44, v0
	v_mov_b32_e32 v45, v0
	v_mov_b32_e32 v46, v0
	v_mov_b32_e32 v47, v0
	v_mov_b32_e32 v56, v0
	v_mov_b32_e32 v57, v0
	v_mov_b32_e32 v58, v0
	v_mov_b32_e32 v59, v0
	v_mov_b32_e32 v60, v0
	v_mov_b32_e32 v61, v0
	v_mov_b32_e32 v62, v0
	v_mov_b32_e32 v63, v0
	v_mov_b32_e32 v64, v0
	v_mov_b32_e32 v65, v0
	v_mov_b32_e32 v66, v0
	v_mov_b32_e32 v67, v0
	v_mov_b32_e32 v68, v0
	v_mov_b32_e32 v69, v0
	v_mov_b32_e32 v70, v0
	v_mov_b32_e32 v71, v0
	v_mov_b32_e32 v80, v0
	v_mov_b32_e32 v81, v0
	v_mov_b32_e32 v82, v0
	v_mov_b32_e32 v83, v0
	v_mov_b32_e32 v84, v0
	v_mov_b32_e32 v85, v0
	v_mov_b32_e32 v86, v0
	v_mov_b32_e32 v87, v0
	v_mov_b32_e32 v96, v0
	v_mov_b32_e32 v97, v0
	v_mov_b32_e32 v98, v0
	v_mov_b32_e32 v99, v0
	v_mov_b32_e32 v100, v0
	v_mov_b32_e32 v101, v0
	v_mov_b32_e32 v102, v0
	v_mov_b32_e32 v103, v0
	v_mov_b32_e32 v112, v0
	v_mov_b32_e32 v113, v0
	v_mov_b32_e32 v114, v0
	v_mov_b32_e32 v115, v0
	v_mov_b32_e32 v116, v0
	v_mov_b32_e32 v117, v0
	v_mov_b32_e32 v118, v0
	v_mov_b32_e32 v119, v0
	v_mov_b32_e32 v72, v0
	v_mov_b32_e32 v73, v0
	v_mov_b32_e32 v74, v0
	v_mov_b32_e32 v75, v0
	v_mov_b32_e32 v76, v0
	v_mov_b32_e32 v77, v0
	v_mov_b32_e32 v78, v0
	v_mov_b32_e32 v79, v0
	v_mov_b32_e32 v88, v0
	v_mov_b32_e32 v89, v0
	v_mov_b32_e32 v90, v0
	v_mov_b32_e32 v91, v0
	v_mov_b32_e32 v92, v0
	v_mov_b32_e32 v93, v0
	v_mov_b32_e32 v94, v0
	v_mov_b32_e32 v95, v0
	v_mov_b32_e32 v104, v0
	v_mov_b32_e32 v105, v0
	v_mov_b32_e32 v106, v0
	v_mov_b32_e32 v107, v0
	v_mov_b32_e32 v108, v0
	v_mov_b32_e32 v109, v0
	v_mov_b32_e32 v110, v0
	v_mov_b32_e32 v111, v0
	v_mov_b32_e32 v120, v0
	v_mov_b32_e32 v121, v0
	v_mov_b32_e32 v122, v0
	v_mov_b32_e32 v123, v0
	v_mov_b32_e32 v124, v0
	v_mov_b32_e32 v125, v0
	v_mov_b32_e32 v126, v0
	v_mov_b32_e32 v127, v0
	.p2align	6

; template <class Epi, class Sched, bool ALIGN_EPI = false, bool SP2 = false>
; __device__ __forceinline__ void gemm_phase(LAS unsigned char* lds, const Gemm g, const Sched S, const Epi E) {
;     ...
; #pragma unroll
;         for (int a = 0; a < 2; ++a)
; #pragma unroll
;             for (int b = 0; b < 2; ++b)
; #pragma unroll
;                 for (int m = 0; m < 4; ++m)
; #pragma unroll
;                     for (int n = 0; n < 2; ++n) acc[a][b][m][n] = (f32x4){0.f, 0.f, 0.f, 0.f};
;         cur = nxt; cA = nA; cB = nB; ++ui;
.LBB0_1849:
	s_ashr_i32 s53, s52, 31
	s_lshl_b64 s[14:15], s[52:53], 20
	s_add_u32 s54, s24, s14
	s_addc_u32 s55, s25, s15
	s_and_b64 s[14:15], s[6:7], exec
	s_cselect_b32 s16, s55, s11
	s_cselect_b32 s17, s54, s10
	s_ashr_i32 s51, s50, 31
	s_lshl_b64 s[14:15], s[50:51], 19
	s_add_u32 s56, s38, s14
	s_addc_u32 s57, s39, s15
	s_and_b64 s[14:15], s[6:7], exec
	s_cselect_b32 s18, s57, s13
	s_cselect_b32 s19, s56, s12
	s_add_u32 s10, s10, 0x80080
	s_addc_u32 s11, s11, 0
	s_add_u32 s22, s12, 0x100
	v_mov_b32_e32 v0, 0
	s_addc_u32 s23, s13, 0
	s_mov_b32 s51, -2
	v_mov_b32_e32 v1, v0
	v_mov_b32_e32 v2, v0
	v_mov_b32_e32 v3, v0
	v_mov_b32_e32 v4, v0
	v_mov_b32_e32 v5, v0
	v_mov_b32_e32 v6, v0
	v_mov_b32_e32 v7, v0
	v_mov_b32_e32 v16, v0
	v_mov_b32_e32 v17, v0
	v_mov_b32_e32 v18, v0
	v_mov_b32_e32 v19, v0
	v_mov_b32_e32 v20, v0
	v_mov_b32_e32 v21, v0
	v_mov_b32_e32 v22, v0
	v_mov_b32_e32 v23, v0
	v_mov_b32_e32 v32, v0
	v_mov_b32_e32 v33, v0
	v_mov_b32_e32 v34, v0
	v_mov_b32_e32 v35, v0
	v_mov_b32_e32 v36, v0
	v_mov_b32_e32 v37, v0
	v_mov_b32_e32 v38, v0
	v_mov_b32_e32 v39, v0
	v_mov_b32_e32 v48, v0
	v_mov_b32_e32 v49, v0
	v_mov_b32_e32 v50, v0
	v_mov_b32_e32 v51, v0
	v_mov_b32_e32 v52, v0
	v_mov_b32_e32 v53, v0
	v_mov_b32_e32 v54, v0
	v_mov_b32_e32 v55, v0
	v_mov_b32_e32 v8, v0
	v_mov_b32_e32 v9, v0
	v_mov_b32_e32 v10, v0
	v_mov_b32_e32 v11, v0
	v_mov_b32_e32 v12, v0
	v_mov_b32_e32 v13, v0
	v_mov_b32_e32 v14, v0
	v_mov_b32_e32 v15, v0
	v_mov_b32_e32 v24, v0
	v_mov_b32_e32 v25, v0
	v_mov_b32_e32 v26, v0
	v_mov_b32_e32 v27, v0
	v_mov_b32_e32 v28, v0
	v_mov_b32_e32 v29, v0
	v_mov_b32_e32 v30, v0
	v_mov_b32_e32 v31, v0
	v_mov_b32_e32 v40, v0
	v_mov_b32_e32 v41, v0
	v_mov_b32_e32 v42, v0
	v_mov_b32_e32 v43, v0
	v_mov_b32_e32 v44, v0
	v_mov_b32_e32 v45, v0
	v_mov_b32_e32 v46, v0
	v_mov_b32_e32 v47, v0
	v_mov_b32_e32 v56, v0
	v_mov_b32_e32 v57, v0
	v_mov_b32_e32 v58, v0
	v_mov_b32_e32 v59, v0
	v_mov_b32_e32 v60, v0
	v_mov_b32_e32 v61, v0
	v_mov_b32_e32 v62, v0
	v_mov_b32_e32 v63, v0
	v_mov_b32_e32 v64, v0
	v_mov_b32_e32 v65, v0
	v_mov_b32_e32 v66, v0
	v_mov_b32_e32 v67, v0
	v_mov_b32_e32 v68, v0
	v_mov_b32_e32 v69, v0
	v_mov_b32_e32 v70, v0
	v_mov_b32_e32 v71, v0
	v_mov_b32_e32 v80, v0
	v_mov_b32_e32 v81, v0
	v_mov_b32_e32 v82, v0
	v_mov_b32_e32 v83, v0
	v_mov_b32_e32 v84, v0
	v_mov_b32_e32 v85, v0
	v_mov_b32_e32 v86, v0
	v_mov_b32_e32 v87, v0
	v_mov_b32_e32 v96, v0
	v_mov_b32_e32 v97, v0
	v_mov_b32_e32 v98, v0
	v_mov_b32_e32 v99, v0
	v_mov_b32_e32 v100, v0
	v_mov_b32_e32 v101, v0
	v_mov_b32_e32 v102, v0
	v_mov_b32_e32 v103, v0
	v_mov_b32_e32 v112, v0
	v_mov_b32_e32 v113, v0
	v_mov_b32_e32 v114, v0
	v_mov_b32_e32 v115, v0
	v_mov_b32_e32 v116, v0
	v_mov_b32_e32 v117, v0
	v_mov_b32_e32 v118, v0
	v_mov_b32_e32 v119, v0
	v_mov_b32_e32 v72, v0
	v_mov_b32_e32 v73, v0
	v_mov_b32_e32 v74, v0
	v_mov_b32_e32 v75, v0
	v_mov_b32_e32 v76, v0
	v_mov_b32_e32 v77, v0
	v_mov_b32_e32 v78, v0
	v_mov_b32_e32 v79, v0
	v_mov_b32_e32 v88, v0
	v_mov_b32_e32 v89, v0
	v_mov_b32_e32 v90, v0
	v_mov_b32_e32 v91, v0
	v_mov_b32_e32 v92, v0
	v_mov_b32_e32 v93, v0
	v_mov_b32_e32 v94, v0
	v_mov_b32_e32 v95, v0
	v_mov_b32_e32 v104, v0
	v_mov_b32_e32 v105, v0
	v_mov_b32_e32 v106, v0
	v_mov_b32_e32 v107, v0
	v_mov_b32_e32 v108, v0
	v_mov_b32_e32 v109, v0
	v_mov_b32_e32 v110, v0
	v_mov_b32_e32 v111, v0
	v_mov_b32_e32 v120, v0
	v_mov_b32_e32 v121, v0
	v_mov_b32_e32 v122, v0
	v_mov_b32_e32 v123, v0
	v_mov_b32_e32 v124, v0
	v_mov_b32_e32 v125, v0
	v_mov_b32_e32 v126, v0
	v_mov_b32_e32 v127, v0
	v_lshl_add_u32 v252, s8, 8, v147
	v_ashrrev_i32_e32 v253, 31, v252
	v_lshl_add_u64 v[254:255], v[252:253], 2, s[42:43]
	global_load_dword v244, v[254:255], off
	global_load_dword v245, v[254:255], off offset:512
	global_load_dword v246, v[254:255], off offset:576
	global_load_dword v247, v[254:255], off offset:640
	global_load_dword v248, v[254:255], off offset:64
	global_load_dword v249, v[254:255], off offset:128
	global_load_dword v250, v[254:255], off offset:192
	global_load_dword v251, v[254:255], off offset:704
	.p2align	6

; template <class Epi, class Sched, bool ALIGN_EPI = false, bool SP2 = false>
; __device__ __forceinline__ void gemm_phase(LAS unsigned char* lds, const Gemm g, const Sched S, const Epi E) {
;     ...
; #pragma unroll
;         for (int a = 0; a < 2; ++a)
; #pragma unroll
;             for (int b = 0; b < 2; ++b)
; #pragma unroll
;                 for (int m = 0; m < 4; ++m)
; #pragma unroll
;                     for (int n = 0; n < 2; ++n) acc[a][b][m][n] = (f32x4){0.f, 0.f, 0.f, 0.f};
;         cur = nxt; cA = nA; cB = nB; ++ui;
.LBB0_1929:
	s_add_u32 s64, s44, 0x100
	v_mov_b32_e32 v0, 0
	s_addc_u32 s65, s45, 0
	s_mov_b32 s66, -2
	v_mov_b32_e32 v1, v0
	v_mov_b32_e32 v2, v0
	v_mov_b32_e32 v3, v0
	v_mov_b32_e32 v4, v0
	v_mov_b32_e32 v5, v0
	v_mov_b32_e32 v6, v0
	v_mov_b32_e32 v7, v0
	v_mov_b32_e32 v16, v0
	v_mov_b32_e32 v17, v0
	v_mov_b32_e32 v18, v0
	v_mov_b32_e32 v19, v0
	v_mov_b32_e32 v20, v0
	v_mov_b32_e32 v21, v0
	v_mov_b32_e32 v22, v0
	v_mov_b32_e32 v23, v0
	v_mov_b32_e32 v32, v0
	v_mov_b32_e32 v33, v0
	v_mov_b32_e32 v34, v0
	v_mov_b32_e32 v35, v0
	v_mov_b32_e32 v36, v0
	v_mov_b32_e32 v37, v0
	v_mov_b32_e32 v38, v0
	v_mov_b32_e32 v39, v0
	v_mov_b32_e32 v48, v0
	v_mov_b32_e32 v49, v0
	v_mov_b32_e32 v50, v0
	v_mov_b32_e32 v51, v0
	v_mov_b32_e32 v52, v0
	v_mov_b32_e32 v53, v0
	v_mov_b32_e32 v54, v0
	v_mov_b32_e32 v55, v0
	v_mov_b32_e32 v8, v0
	v_mov_b32_e32 v9, v0
	v_mov_b32_e32 v10, v0
	v_mov_b32_e32 v11, v0
	v_mov_b32_e32 v12, v0
	v_mov_b32_e32 v13, v0
	v_mov_b32_e32 v14, v0
	v_mov_b32_e32 v15, v0
	v_mov_b32_e32 v24, v0
	v_mov_b32_e32 v25, v0
	v_mov_b32_e32 v26, v0
	v_mov_b32_e32 v27, v0
	v_mov_b32_e32 v28, v0
	v_mov_b32_e32 v29, v0
	v_mov_b32_e32 v30, v0
	v_mov_b32_e32 v31, v0
	v_mov_b32_e32 v40, v0
	v_mov_b32_e32 v41, v0
	v_mov_b32_e32 v42, v0
	v_mov_b32_e32 v43, v0
	v_mov_b32_e32 v44, v0
	v_mov_b32_e32 v45, v0
	v_mov_b32_e32 v46, v0
	v_mov_b32_e32 v47, v0
	v_mov_b32_e32 v56, v0
	v_mov_b32_e32 v57, v0
	v_mov_b32_e32 v58, v0
	v_mov_b32_e32 v59, v0
	v_mov_b32_e32 v60, v0
	v_mov_b32_e32 v61, v0
	v_mov_b32_e32 v62, v0
	v_mov_b32_e32 v63, v0
	v_mov_b32_e32 v64, v0
	v_mov_b32_e32 v65, v0
	v_mov_b32_e32 v66, v0
	v_mov_b32_e32 v67, v0
	v_mov_b32_e32 v68, v0
	v_mov_b32_e32 v69, v0
	v_mov_b32_e32 v70, v0
	v_mov_b32_e32 v71, v0
	v_mov_b32_e32 v80, v0
	v_mov_b32_e32 v81, v0
	v_mov_b32_e32 v82, v0
	v_mov_b32_e32 v83, v0
	v_mov_b32_e32 v84, v0
	v_mov_b32_e32 v85, v0
	v_mov_b32_e32 v86, v0
	v_mov_b32_e32 v87, v0
	v_mov_b32_e32 v96, v0
	v_mov_b32_e32 v97, v0
	v_mov_b32_e32 v98, v0
	v_mov_b32_e32 v99, v0
	v_mov_b32_e32 v100, v0
	v_mov_b32_e32 v101, v0
	v_mov_b32_e32 v102, v0
	v_mov_b32_e32 v103, v0
	v_mov_b32_e32 v112, v0
	v_mov_b32_e32 v113, v0
	v_mov_b32_e32 v114, v0
	v_mov_b32_e32 v115, v0
	v_mov_b32_e32 v116, v0
	v_mov_b32_e32 v117, v0
	v_mov_b32_e32 v118, v0
	v_mov_b32_e32 v119, v0
	v_mov_b32_e32 v72, v0
	v_mov_b32_e32 v73, v0
	v_mov_b32_e32 v74, v0
	v_mov_b32_e32 v75, v0
	v_mov_b32_e32 v76, v0
	v_mov_b32_e32 v77, v0
	v_mov_b32_e32 v78, v0
	v_mov_b32_e32 v79, v0
	v_mov_b32_e32 v88, v0
	v_mov_b32_e32 v89, v0
	v_mov_b32_e32 v90, v0
	v_mov_b32_e32 v91, v0
	v_mov_b32_e32 v92, v0
	v_mov_b32_e32 v93, v0
	v_mov_b32_e32 v94, v0
	v_mov_b32_e32 v95, v0
	v_mov_b32_e32 v104, v0
	v_mov_b32_e32 v105, v0
	v_mov_b32_e32 v106, v0
	v_mov_b32_e32 v107, v0
	v_mov_b32_e32 v108, v0
	v_mov_b32_e32 v109, v0
	v_mov_b32_e32 v110, v0
	v_mov_b32_e32 v111, v0
	v_mov_b32_e32 v120, v0
	v_mov_b32_e32 v121, v0
	v_mov_b32_e32 v122, v0
	v_mov_b32_e32 v123, v0
	v_mov_b32_e32 v124, v0
	v_mov_b32_e32 v125, v0
	v_mov_b32_e32 v126, v0
	v_mov_b32_e32 v127, v0
	.p2align	6
